# one static priority raise for waves 4-7 at the start of the attention/S5/conv phases and the cross-attention phase (strategy 4), reset by the next GEMM loop
# baseline (speedup 1.0000x reference)
; __device__ __forceinline__ PP get_pp() { PP q = (PP)__builtin_amdgcn_kernarg_segment_ptr(); asm volatile("" : "+s"(q)); return q; }
; __device__ __forceinline__ int tid_fresh() { int t = threadIdx.x; asm volatile("" : "+v"(t)); return t; }
; __device__ __forceinline__ void dil_issue(PP p, const DilUnit& q, DilRegs& R, int tid) {
;     const bf16_t* proj = (const bf16_t*)(p->ws + WS_PROJ);
; #pragma unroll
;     for (int i = 0; i < 4; ++i) {
;         const int bi = 2 * (tid >> 3) + (i & 1) + 128 * (i >> 1), ch = tid & 7, sp = 128 * (q.n - 1) + bi;
;         R.kv[i] = (u32x4){0u, 0u, 0u, 0u}; R.vv[i] = R.kv[i];
;         if (sp >= 0) { const size_t hp = ((size_t)((q.b * 8 + q.h) * SEQ + sp * q.d + q.r)) * 64 + ch * 8; R.kv[i] = *(const u32x4*)(proj + PJ_QKV + (size_t)1 * 4 * 8 * SEQ * 64 + hp); R.vv[i] = *(const u32x4*)(proj + PJ_QKV + (size_t)2 * 4 * 8 * SEQ * 64 + hp); }
; __device__ __forceinline__ void dil_attn_units(unsigned char* shm, int first, int stride) {
;     const int tid = tid_fresh();
;     if (first >= 1536) return;
;     bf16x8 qcur[2];
;     { PP p = get_pp(); DilRegs R; const DilUnit q = dil_decode(first); dil_issue(p, q, R, tid); dil_stage(R, shm, tid); qcur[0] = R.qf[0]; qcur[1] = R.qf[1]; }
.LBB0_505:
	s_or_b64 exec, exec, s[8:9]
	s_waitcnt lgkmcnt(0)
	s_barrier
	v_readfirstlane_b32 s98, v222
	s_nop 3
	s_cmp_ge_u32 s98, 0x100
	s_cbranch_scc0 .Lprio1_done
	s_setprio 1
.Lprio1_done:
	v_mov_b32_e32 v51, v222
	s_cmpk_lt_i32 s30, 0x600
	s_cbranch_scc0 .LBB0_548
	s_and_b32 s2, s30, 7
	s_mulk_i32 s2, 0xc0
	s_ashr_i32 s3, s30, 3
	s_add_i32 s2, s2, s3
	s_ashr_i32 s13, s2, 31
	s_lshr_b32 s13, s13, 23
	s_add_i32 s13, s2, s13
	s_and_b32 s13, s13, 0xfe00
	s_add_i32 s12, s2, 0x1ff
	s_and_b32 s3, s2, 0xfffffe00
	s_sub_i32 s2, s2, s13
	s_sext_i32_i16 s13, s2
	s_lshr_b32 s13, s13, 15
	s_bfe_u32 s14, s13, 0x4000c
	s_add_i32 s14, s2, s14
	s_bfe_u32 s16, s14, 0xc0004
	s_and_b32 s14, s14, 0xfff0
	s_sub_i32 s17, s2, s14
	s_bfe_i32 s14, s16, 0x80000
	s_bfe_u32 s14, s14, 0x3000c
	s_bfe_u32 s13, s13, 0x70009
	s_add_i32 s14, s16, s14
	s_add_i32 s2, s2, s13
	s_and_b32 s14, s14, 0xf8
	s_sext_i32_i16 s2, s2
	s_sub_i32 s14, s16, s14
	s_ashr_i32 s18, s2, 7
	s_cmpk_eq_i32 s3, 0x200
	s_cselect_b64 s[28:29], -1, 0
	s_and_b64 s[2:3], s[28:29], exec
	s_cselect_b32 s13, 4, 1
	s_cmpk_lt_u32 s12, 0x3ff
	s_cselect_b64 s[34:35], -1, 0
	s_and_b64 s[2:3], s[34:35], exec
	s_cselect_b32 s12, 16, s13
	s_sext_i32_i8 s2, s12
	v_cvt_f32_i32_e32 v0, s2
	s_sext_i32_i8 s3, s17
	v_cvt_f32_i32_e32 v2, s3
	s_xor_b32 s2, s3, s2
	v_rcp_iflag_f32_e32 v3, v0
	s_ashr_i32 s2, s2, 30
	s_or_b32 s13, s2, 1
	s_mov_b64 s[8:9], s[0:1]
	v_mul_f32_e32 v3, v2, v3
	v_trunc_f32_e32 v3, v3
	v_fma_f32 v2, -v3, v0, v2
	v_cvt_i32_f32_e32 v3, v3
	v_cmp_ge_f32_e64 s[2:3], |v2|, |v0|
	s_and_b64 s[2:3], s[2:3], exec
	s_cselect_b32 s2, s13, 0
	v_readfirstlane_b32 s3, v3
	s_add_i32 s2, s3, s2
	s_sext_i32_i8 s24, s2
	s_mul_i32 s2, s2, s12
	s_load_dwordx2 s[12:13], s[8:9], 0x110
	s_sub_i32 s2, s17, s2
	s_sext_i32_i8 s16, s2
	v_ashrrev_i32_e32 v0, 2, v51
	v_and_b32_e32 v58, -2, v0
	s_waitcnt lgkmcnt(0)
	s_add_u32 s2, s12, 0x20600000
	s_addc_u32 s3, s13, 0
	s_add_u32 s20, s12, 0x20e00000
	v_add_u32_e32 v59, 0xffffff80, v58
	v_lshlrev_b32_e32 v2, 3, v51
	s_addc_u32 s21, s13, 0
	s_lshl_b32 s25, s16, 7
	v_and_b32_e32 v60, 56, v2
	v_add_u32_e32 v2, s25, v59
	s_sext_i32_i8 s14, s14
	v_cmp_lt_i32_e32 vcc, -1, v2
	v_mov_b32_e32 v14, 0
	v_mov_b32_e32 v18, 0
	v_mov_b32_e32 v19, 0
	v_mov_b32_e32 v20, 0
	v_mov_b32_e32 v21, 0
	v_mov_b32_e32 v10, 0
	v_mov_b32_e32 v11, 0
	v_mov_b32_e32 v12, 0
	v_mov_b32_e32 v13, 0
	s_and_saveexec_b64 s[22:23], vcc
	s_cbranch_execz .LBB0_508
	s_lshl_b32 s16, s18, 14
	s_lshl_b32 s17, s14, 11
	s_add_i32 s36, s17, s16
	s_and_b64 s[16:17], s[28:29], exec
	s_cselect_b32 s37, 2, 4
	s_and_b64 s[16:17], s[34:35], exec
	s_cselect_b32 s16, 0, s37
	v_lshlrev_b32_e32 v2, s16, v2
	s_add_i32 s36, s36, s24
	v_add_u32_e32 v2, s36, v2
	v_ashrrev_i32_e32 v3, 31, v2
	v_lshlrev_b64 v[2:3], 7, v[2:3]
	v_lshl_or_b32 v2, v60, 1, v2
	v_lshl_add_u64 v[4:5], s[2:3], 0, v[2:3]
	v_lshl_add_u64 v[2:3], s[20:21], 0, v[2:3]
	global_load_dwordx4 v[18:21], v[4:5], off
	global_load_dwordx4 v[10:13], v[2:3], off

; __device__ __forceinline__ PP get_pp() { PP q = (PP)__builtin_amdgcn_kernarg_segment_ptr(); asm volatile("" : "+s"(q)); return q; }
; __device__ __forceinline__ int tid_fresh() { int t = threadIdx.x; asm volatile("" : "+v"(t)); return t; }
; __device__ __forceinline__ int bid_fresh() { int t = blockIdx.x; asm volatile("" : "+s"(t)); return t; }
; __device__ __forceinline__ void cross_attn_unit(PP p, unsigned char* shm, int u, int l) {
;     const bf16_t* kvb = (const bf16_t*)(p->ws + WS_KV);
;     bf16_t* Ks = (bf16_t*)(shm + AT_KS); bf16_t* Vt = (bf16_t*)(shm + AT_VT);
;     const int tid = tid_fresh(), w = tid >> 6, lane = tid & 63, fr = lane & 15, quad = lane >> 4;
;     const int b = u / 64, xh = (u / 16) % 4, qt = u % 16;
;     const size_t rowq = (size_t)(b * SEQ + qt * 128 + 16 * w + fr);
;     float qs;
;     { const float* sp = (const float*)(p->ws + WS_SS) + ((size_t)(1 + 3 * l) * T + rowq) * 32 + quad * 8;
;       const f32x4 a0 = *(const f32x4*)sp, a1 = *(const f32x4*)(sp + 4);
;       float t = ((a0[0] + a0[1]) + (a0[2] + a0[3])) + ((a1[0] + a1[1]) + (a1[2] + a1[3]));
;       t += __shfl_xor(t, 16); t += __shfl_xor(t, 32);
;       qs = (0.08838834764831845f * 1.4426950408889634f) / sqrtf(t * (1.0f / D) + EPS); }
; __global__ void __launch_bounds__(512, 2) hymba_fwd(Params p_unused) {
;     ...
;         for (int rep = 0; rep < P9_REPS; ++rep) for (int it = bid_fresh(); it < 256; it += gridDim.x) cross_attn_unit(get_pp(), shm, it, l);
.LBB0_1178:
	s_or_b64 exec, exec, s[8:9]
	s_mov_b32 s2, s30
	s_waitcnt lgkmcnt(0)
	s_barrier
	v_readfirstlane_b32 s98, v222
	s_nop 3
	s_cmp_ge_u32 s98, 0x100
	s_cbranch_scc0 .Lprio6_done
	s_setprio 1
.Lprio6_done:
	s_cmpk_gt_i32 s2, 0xff
	s_mov_b32 s22, 0xff61b1e6
	s_mov_b32 s23, 0x3e0293ee
	s_movk_i32 s24, 0x110
	v_readlane_b32 s28, v255, 20
	v_readlane_b32 s29, v255, 21
	s_cbranch_scc1 .LBB0_1181
	s_lshl_b32 s8, s28, 10
	s_lshl_b32 s3, s2, 7
	s_lshl_b32 s14, s66, 7
	s_lshl_b32 s16, s8, 1
